# waves 1-7 touch the next phase's first weight K-tiles before the barrier rendezvous (seams 2-5)
# speedup vs baseline: 1.0076x; 1.0076x over previous
; #define SEAM(k) do { if (IN(k) && IN((k) + 1)) { xcd_barrier(bar); } } while (0)
; __device__ __forceinline__ void xcd_barrier(const XcdBarrier& b) {
;     asm volatile("s_waitcnt vmcnt(0)" ::: "memory");
;     __syncthreads();
; __global__ void __launch_bounds__(NTHREADS, 2) hybrid_fwd(Args args) {
;     ...
;     SEAM(2);
;     if (IN(3)) {
;         pg8::Gemm g{(const pg8::bf16_t*)(ws + WS_QS), (const pg8::bf16_t*)(ws + WS_WHS), M, D, 1024, 2048}; pg8::SplitOrder S; S.s.init(M, D, G, (int)blockIdx.x);
.LBB0_723:
	s_cmp_gt_i32 s75, 3
	s_cselect_b64 s[0:1], -1, 0
	s_and_b64 s[2:3], s[2:3], s[0:1]
	s_andn2_b64 vcc, exec, s[2:3]
	s_cbranch_vccnz .LBB0_777
	s_waitcnt vmcnt(0)
	s_waitcnt vmcnt(0) lgkmcnt(0)
	s_barrier
	v_readfirstlane_b32 s4, v188
	s_lshr_b32 s4, s4, 6
	s_cmp_eq_u32 s4, 0
	s_cbranch_scc1 .Lmy_bpf_2
	s_cmpk_lg_i32 s84, 0x100
	s_cbranch_scc1 .Lmy_bpf_2
	s_lshr_b32 s5, s33, 6
	s_mul_i32 s5, s5, 0x100000
	s_add_u32 s6, s72, 0x1400000
	s_addc_u32 s7, s73, 0
	s_add_u32 s6, s6, s5
	s_addc_u32 s7, s7, 0
	v_add_u32_e32 v0, 0xffffffc0, v188
	v_lshrrev_b32_e32 v1, 1, v0
	v_and_b32_e32 v2, 1, v0
	v_lshlrev_b32_e32 v2, 7, v2
	v_mul_u32_u24_e32 v3, 0x1000, v1
	v_add_u32_e32 v3, v3, v2
	global_load_dword v4, v3, s[6:7]
	v_add_u32_e32 v1, 0xe0, v1
	v_min_u32_e32 v1, 0xff, v1
	v_mul_u32_u24_e32 v3, 0x1000, v1
	v_add_u32_e32 v3, v3, v2
	global_load_dword v5, v3, s[6:7]

; #define SEAM(k) do { if (IN(k) && IN((k) + 1)) { xcd_barrier(bar); } } while (0)
; __device__ __forceinline__ void xcd_barrier(const XcdBarrier& b) {
;     asm volatile("s_waitcnt vmcnt(0)" ::: "memory");
;     __syncthreads();
; __global__ void __launch_bounds__(NTHREADS, 2) hybrid_fwd(Args args) {
;     ...
;     SEAM(3);
;     if (IN(4)) {
;         pg8::Gemm g{(const pg8::bf16_t*)(ws + WS_MIXED), (const pg8::bf16_t*)(ws + WS_WO), M, D, D, D}; pg8::StaticOrder S; S.init(M, D, G, (int)blockIdx.x);
.LBB0_808:
	s_cmp_gt_i32 s75, 4
	s_cselect_b64 s[2:3], -1, 0
	s_and_b64 s[0:1], s[0:1], s[2:3]
	s_andn2_b64 vcc, exec, s[0:1]
	s_cbranch_vccnz .LBB0_862
	s_waitcnt vmcnt(0)
	s_waitcnt vmcnt(0) lgkmcnt(0)
	s_barrier
	v_readfirstlane_b32 s4, v188
	s_lshr_b32 s4, s4, 6
	s_cmp_eq_u32 s4, 0
	s_cbranch_scc1 .Lmy_bpf_3
	s_cmpk_lg_i32 s84, 0x100
	s_cbranch_scc1 .Lmy_bpf_3
	s_lshr_b32 s5, s33, 6
	s_mul_i32 s5, s5, 0x80000
	s_add_u32 s6, s72, 0x1800000
	s_addc_u32 s7, s73, 0
	s_add_u32 s6, s6, s5
	s_addc_u32 s7, s7, 0
	v_add_u32_e32 v0, 0xffffffc0, v188
	v_lshrrev_b32_e32 v1, 1, v0
	v_and_b32_e32 v2, 1, v0
	v_lshlrev_b32_e32 v2, 7, v2
	v_mul_u32_u24_e32 v3, 0x800, v1
	v_add_u32_e32 v3, v3, v2
	global_load_dword v4, v3, s[6:7]
	v_add_u32_e32 v1, 0xe0, v1
	v_min_u32_e32 v1, 0xff, v1
	v_mul_u32_u24_e32 v3, 0x800, v1
	v_add_u32_e32 v3, v3, v2
	global_load_dword v5, v3, s[6:7]

; #define SEAM(k) do { if (IN(k) && IN((k) + 1)) { xcd_barrier(bar); } } while (0)
; __device__ __forceinline__ void xcd_barrier(const XcdBarrier& b) {
;     asm volatile("s_waitcnt vmcnt(0)" ::: "memory");
;     __syncthreads();
; __global__ void __launch_bounds__(NTHREADS, 2) hybrid_fwd(Args args) {
;     ...
;     SEAM(4);
;     if (IN(5)) {
;         pg8::Gemm g{(const pg8::bf16_t*)(ws + WS_X1B), (const pg8::bf16_t*)(ws + WS_WF1), M, 2 * FFH, D, D}; pg8::StaticOrder S; S.init(M, 2 * FFH, G, (int)blockIdx.x);
.LBB0_905:
	s_cmp_gt_i32 s75, 5
	s_cselect_b64 s[2:3], -1, 0
	s_and_b64 s[0:1], s[0:1], s[2:3]
	s_andn2_b64 vcc, exec, s[0:1]
	s_cbranch_vccnz .LBB0_959
	s_waitcnt vmcnt(0)
	s_waitcnt vmcnt(0) lgkmcnt(0)
	s_barrier
	v_readfirstlane_b32 s4, v188
	s_lshr_b32 s4, s4, 6
	s_cmp_eq_u32 s4, 0
	s_cbranch_scc1 .Lmy_bpf_4
	s_cmpk_lg_i32 s84, 0x100
	s_cbranch_scc1 .Lmy_bpf_4
	s_lshr_b32 s5, s33, 6
	s_mul_i32 s5, s5, 0x80000
	s_add_u32 s6, s72, 0x1a00000
	s_addc_u32 s7, s73, 0
	s_add_u32 s6, s6, s5
	s_addc_u32 s7, s7, 0
	v_add_u32_e32 v0, 0xffffffc0, v188
	v_lshrrev_b32_e32 v1, 1, v0
	v_and_b32_e32 v2, 1, v0
	v_lshlrev_b32_e32 v2, 7, v2
	v_mul_u32_u24_e32 v3, 0x800, v1
	v_add_u32_e32 v3, v3, v2
	global_load_dword v4, v3, s[6:7]
	v_add_u32_e32 v1, 0xe0, v1
	v_min_u32_e32 v1, 0xff, v1
	v_mul_u32_u24_e32 v3, 0x800, v1
	v_add_u32_e32 v3, v3, v2
	global_load_dword v5, v3, s[6:7]

; #define SEAM(k) do { if (IN(k) && IN((k) + 1)) { xcd_barrier(bar); } } while (0)
; __device__ __forceinline__ void xcd_barrier(const XcdBarrier& b) {
;     asm volatile("s_waitcnt vmcnt(0)" ::: "memory");
;     __syncthreads();
; __global__ void __launch_bounds__(NTHREADS, 2) hybrid_fwd(Args args) {
;     ...
;     SEAM(5);
;     if (IN(6)) {
;         pg8::Gemm g{(const pg8::bf16_t*)(ws + WS_ACT), (const pg8::bf16_t*)(ws + WS_WF2), M, D, FFH, FFH}; pg8::StaticOrder S; S.init(M, D, G, (int)blockIdx.x);
.LBB0_976:
	s_cmp_gt_i32 s75, 6
	s_cselect_b64 s[2:3], -1, 0
	s_and_b64 s[0:1], s[0:1], s[2:3]
	s_andn2_b64 vcc, exec, s[0:1]
	s_cbranch_vccnz .LBB0_1030
	s_waitcnt vmcnt(0)
	s_waitcnt vmcnt(0) lgkmcnt(0)
	s_barrier
	v_readfirstlane_b32 s4, v188
	s_lshr_b32 s4, s4, 6
	s_cmp_eq_u32 s4, 0
	s_cbranch_scc1 .Lmy_bpf_5
	s_cmpk_lg_i32 s84, 0x100
	s_cbranch_scc1 .Lmy_bpf_5
	s_lshr_b32 s5, s33, 6
	s_mul_i32 s5, s5, 0x160000
	s_add_u32 s6, s72, 0x2500000
	s_addc_u32 s7, s73, 0
	s_add_u32 s6, s6, s5
	s_addc_u32 s7, s7, 0
	v_add_u32_e32 v0, 0xffffffc0, v188
	v_lshrrev_b32_e32 v1, 1, v0
	v_and_b32_e32 v2, 1, v0
	v_lshlrev_b32_e32 v2, 7, v2
	v_mul_u32_u24_e32 v3, 0x1600, v1
	v_add_u32_e32 v3, v3, v2
	global_load_dword v4, v3, s[6:7]
	v_add_u32_e32 v1, 0xe0, v1
	v_min_u32_e32 v1, 0xff, v1
	v_mul_u32_u24_e32 v3, 0x1600, v1
	v_add_u32_e32 v3, v3, v2
	global_load_dword v5, v3, s[6:7]
